# v24 + 100x64-cycle stagger of odd wave slots at gemm_res phase entries
# baseline (speedup 1.0000x reference)
; #define TIDX tid_()
; #define LAS __attribute__((address_space(3)))
; DEVI int wave_() { return __builtin_amdgcn_readfirstlane(tid_() >> 6); }
; DEVI void gemm_issue0(const bf16_t* Ab, int lda, const bf16_t* Btile, int ldb, bf16_t* smem) {
;     const int tid = TIDX, wave = wave_();
;     const unsigned lds0 = (unsigned)(size_t)((LAS unsigned char*)smem) + (unsigned)wave * 1024u;
;     unsigned va[4], vb[4];
; #pragma unroll
;     for (int j = 0; j < 4; ++j) {
;         const int R = j * 32 + (tid >> 3), c = (tid & 7) ^ ((R >> 1) & 7);
;         va[j] = (unsigned)(((size_t)R * lda + c * 8) * 2);
;         vb[j] = (unsigned)(((size_t)R * ldb + c * 8) * 2);
;     }
;     glds_tile8(va, vb, Ab, Btile, __builtin_amdgcn_readfirstlane(lds0));
; }
; DEVI void phase_gemm_res(const Params& p, const bf16_t* A, int K, const bf16_t* Bt, const float* xraw, int lnidx, float bscale, bf16_t* smem) {
;     float* hbuf = (float*)(p.ws + OFF_H);
;     const f32x2v* stats = (const f32x2v*)(p.ws + OFF_STATS);
;     const float* lg = p.ln_g + (size_t)lnidx * D_;
;     const float* lb = p.ln_b + (size_t)lnidx * D_;
;     const int lane = TIDX & 63, wave = wave_(), wr = wave >> 1, wc = wave & 1, l16 = lane & 15, quad = lane >> 4;
;     int tm, tn;
;     bool have = tile_map(0, 8, tm, tn);
;     if (have) gemm_issue0(A + (size_t)tm * 128 * K, K, Bt + (size_t)tn * 128 * K, K, smem);
.LBB0_205:
	s_andn2_b64 vcc, exec, s[14:15]
	s_cbranch_vccnz .LBB0_224
	s_getreg_b32 s6, hwreg(HW_REG_HW_ID, 0, 4)
	s_and_b32 s6, s6, 1
	s_cmp_eq_u32 s6, 0
	s_cbranch_scc1 .Lgr10_nosleep
	s_sleep 100
.Lgr10_nosleep:
	s_add_u32 s6, s8, 0xe218000
	s_addc_u32 s10, s9, 0
	s_add_u32 s11, s73, 0x24c0000
	s_addc_u32 s13, s72, 0
	v_readlane_b32 s14, v220, 1
	v_readlane_b32 s15, v220, 2
	s_mul_i32 s24, s14, 3
	s_add_u32 s14, s8, 0x15e1c000
	s_addc_u32 s15, s9, 0
	s_ashr_i32 s25, s24, 31
	s_mov_b32 s7, s52
	v_readlane_b32 s40, v223, 62
	s_lshl_b64 s[26:27], s[24:25], 12
	v_readlane_b32 s42, v222, 0
	v_readlane_b32 s43, v222, 1
	s_add_u32 s24, s42, s26
	v_readlane_b32 s44, v222, 2
	s_addc_u32 s25, s43, s27
	v_readlane_b32 s45, v222, 3
	s_add_u32 s26, s44, s26
	v_readlane_b32 s41, v223, 63
	s_addc_u32 s27, s45, s27
	s_ashr_i32 s39, s38, 31
	s_and_b32 s28, s22, 64
	s_lshl_b64 s[40:41], s[38:39], 18
	s_add_u32 s40, s6, s40
	s_addc_u32 s41, s10, s41
	s_ashr_i32 s31, s30, 31
	v_mov_b32_e32 v2, v133
	s_lshl_b64 s[42:43], s[30:31], 18
	v_mov_b32_e32 v3, v133
	v_lshrrev_b32_e32 v4, 4, v2
	s_add_u32 s42, s11, s42
	v_xor_b32_e32 v4, v4, v2
	v_lshlrev_b32_e32 v2, 8, v2
	v_readfirstlane_b32 s17, v3
	s_addc_u32 s43, s13, s43
	v_and_b32_e32 v2, 0xfffff800, v2
	v_lshlrev_b32_e32 v4, 4, v4
	s_lshl_b32 s17, s17, 4
	s_ashr_i32 s22, s22, 1
	v_and_or_b32 v2, v4, s33, v2
	s_and_b32 s17, s17, 0xfffffc00
	s_andn2_b32 s22, s22, 63
	v_add_u32_e32 v4, 0x10000, v2
	v_add_u32_e32 v5, 0x20000, v2
	v_add_u32_e32 v6, 0x30000, v2
	s_mov_b32 s31, m0
	s_mov_b32 m0, s17
	s_nop 0
	global_load_lds_dwordx4 v2, s[40:41]
	s_add_u32 m0, m0, 0x1000
	s_nop 0
	global_load_lds_dwordx4 v4, s[40:41]
	s_add_u32 m0, m0, 0x1000
	s_nop 0
	global_load_lds_dwordx4 v5, s[40:41]
	s_add_u32 m0, m0, 0x1000
	s_nop 0
	global_load_lds_dwordx4 v6, s[40:41]
	s_add_u32 m0, m0, 0x1000
	s_nop 0
	global_load_lds_dwordx4 v2, s[42:43]
	s_add_u32 m0, m0, 0x1000
	s_nop 0
	global_load_lds_dwordx4 v4, s[42:43]
	s_add_u32 m0, m0, 0x1000
	s_nop 0
	global_load_lds_dwordx4 v5, s[42:43]
	s_add_u32 m0, m0, 0x1000
	s_nop 0
	global_load_lds_dwordx4 v6, s[42:43]
	s_mov_b32 m0, s31
	s_ashr_i32 s17, s4, 3
	v_and_or_b32 v104, v0, 15, s22
	v_lshrrev_b32_e32 v0, 2, v0
	s_lshl_b32 s22, s28, 2
	v_and_b32_e32 v0, 12, v0
	s_add_u32 s40, s8, s22
	v_or_b32_e32 v105, s28, v0
	s_addc_u32 s41, s9, 0
	v_lshlrev_b32_e32 v0, 2, v0
	v_readlane_b32 s52, v222, 10
	v_lshl_add_u64 v[2:3], s[40:41], 0, v[0:1]
	s_mov_b64 s[40:41], 0xa218000
	s_mov_b32 s52, s7
	v_lshl_add_u64 v[66:67], v[2:3], 0, s[40:41]
	s_mov_b32 s22, 0
	v_readlane_b32 s46, v222, 4
	v_readlane_b32 s47, v222, 5
	v_readlane_b32 s48, v222, 6
	v_readlane_b32 s49, v222, 7
	v_readlane_b32 s50, v222, 8
	v_readlane_b32 s51, v222, 9
	v_readlane_b32 s53, v222, 11
	v_readlane_b32 s54, v222, 12
	v_readlane_b32 s55, v222, 13
	s_branch .LBB0_208

; #define TIDX tid_()
; #define LAS __attribute__((address_space(3)))
; DEVI int wave_() { return __builtin_amdgcn_readfirstlane(tid_() >> 6); }
; DEVI void gemm_issue0(const bf16_t* Ab, int lda, const bf16_t* Btile, int ldb, bf16_t* smem) {
;     const int tid = TIDX, wave = wave_();
;     const unsigned lds0 = (unsigned)(size_t)((LAS unsigned char*)smem) + (unsigned)wave * 1024u;
;     unsigned va[4], vb[4];
; #pragma unroll
;     for (int j = 0; j < 4; ++j) {
;         const int R = j * 32 + (tid >> 3), c = (tid & 7) ^ ((R >> 1) & 7);
;         va[j] = (unsigned)(((size_t)R * lda + c * 8) * 2);
;         vb[j] = (unsigned)(((size_t)R * ldb + c * 8) * 2);
;     }
;     glds_tile8(va, vb, Ab, Btile, __builtin_amdgcn_readfirstlane(lds0));
; }
; DEVI void phase_gemm_res(const Params& p, const bf16_t* A, int K, const bf16_t* Bt, const float* xraw, int lnidx, float bscale, bf16_t* smem) {
;     float* hbuf = (float*)(p.ws + OFF_H);
;     const f32x2v* stats = (const f32x2v*)(p.ws + OFF_STATS);
;     const float* lg = p.ln_g + (size_t)lnidx * D_;
;     const float* lb = p.ln_b + (size_t)lnidx * D_;
;     const int lane = TIDX & 63, wave = wave_(), wr = wave >> 1, wc = wave & 1, l16 = lane & 15, quad = lane >> 4;
;     int tm, tn;
;     bool have = tile_map(0, 8, tm, tn);
;     if (have) gemm_issue0(A + (size_t)tm * 128 * K, K, Bt + (size_t)tn * 128 * K, K, smem);
.LBB0_753:
	s_andn2_b64 vcc, exec, s[10:11]
	s_cbranch_vccnz .LBB0_776
	s_getreg_b32 s38, hwreg(HW_REG_HW_ID, 0, 4)
	s_and_b32 s38, s38, 1
	s_cmp_eq_u32 s38, 0
	s_cbranch_scc1 .Lgr28_nosleep
	s_sleep 100
.Lgr28_nosleep:
	s_cmp_eq_u32 s60, 11
	s_mov_b32 s6, 0x1b80000
	s_cselect_b32 s10, s6, 0x1600000
	s_add_u32 s13, s73, s10
	s_addc_u32 s17, s72, 0
	s_add_u32 s22, s8, 0x10218000
	s_addc_u32 s28, s9, 0
	s_add_u32 s10, s8, 0xa218000
	s_addc_u32 s11, s9, 0
	s_add_u32 s14, s8, 0x15e1c000
	s_addc_u32 s15, s9, 0
	s_ashr_i32 s25, s24, 31
	v_readlane_b32 s44, v223, 62
	s_lshl_b64 s[26:27], s[24:25], 12
	v_readlane_b32 s46, v222, 0
	v_readlane_b32 s47, v222, 1
	s_add_u32 s24, s46, s26
	v_readlane_b32 s48, v222, 2
	s_addc_u32 s25, s47, s27
	v_readlane_b32 s49, v222, 3
	s_add_u32 s26, s48, s26
	s_addc_u32 s27, s49, s27
	s_and_b32 s35, s34, 64
	s_add_i32 s38, s74, -14
	s_cmp_lt_u32 s38, 0xffffffe7
	s_cselect_b64 s[38:39], -1, 0
	s_or_b64 s[30:31], s[38:39], s[30:31]
	s_mul_i32 s38, s41, 0xb0000
	v_mov_b32_e32 v2, v133
	s_mul_hi_i32 s39, s41, 0xb0000
	s_add_u32 s38, s22, s38
	s_mul_i32 s42, s40, 0x58000
	s_addc_u32 s39, s28, s39
	v_lshrrev_b32_e32 v5, 4, v2
	s_ashr_i32 s43, s42, 31
	v_lshrrev_b32_e32 v4, 3, v2
	v_xor_b32_e32 v2, v5, v2
	s_movk_i32 s44, 0xb00
	s_lshl_b64 s[42:43], s[42:43], 1
	v_mov_b32_e32 v3, v133
	v_lshlrev_b32_e32 v2, 3, v2
	v_mul_lo_u32 v4, v4, s44
	s_add_u32 s42, s13, s42
	v_and_or_b32 v2, v2, 56, v4
	v_readfirstlane_b32 s46, v3
	s_addc_u32 s43, s17, s43
	v_lshlrev_b32_e32 v2, 1, v2
	s_lshl_b32 s46, s46, 4
	v_add_u32_e32 v4, 0x2c000, v2
	v_add_u32_e32 v5, 0x58000, v2
	v_add_u32_e32 v6, 0x84000, v2
	s_and_b32 s46, s46, 0xfffffc00
	s_mov_b32 s47, m0
	s_mov_b32 m0, s46
	s_nop 0
	global_load_lds_dwordx4 v2, s[38:39]
	s_add_u32 m0, m0, 0x1000
	s_nop 0
	global_load_lds_dwordx4 v4, s[38:39]
	s_add_u32 m0, m0, 0x1000
	s_nop 0
	global_load_lds_dwordx4 v5, s[38:39]
	s_add_u32 m0, m0, 0x1000
	s_nop 0
	global_load_lds_dwordx4 v6, s[38:39]
	s_add_u32 m0, m0, 0x1000
	s_nop 0
	global_load_lds_dwordx4 v2, s[42:43]
	s_add_u32 m0, m0, 0x1000
	s_nop 0
	global_load_lds_dwordx4 v4, s[42:43]
	s_add_u32 m0, m0, 0x1000
	s_nop 0
	global_load_lds_dwordx4 v5, s[42:43]
	s_add_u32 m0, m0, 0x1000
	s_nop 0
	global_load_lds_dwordx4 v6, s[42:43]
	s_mov_b32 m0, s47
	v_readlane_b32 s38, v222, 14
	s_ashr_i32 s34, s34, 1
	v_readlane_b32 s39, v222, 15
	s_andn2_b32 s34, s34, 63
	s_ashr_i32 s42, s4, 3
	s_nor_b64 s[30:31], s[30:31], s[38:39]
	v_and_or_b32 v67, v0, 15, s34
	v_lshrrev_b32_e32 v0, 2, v0
	s_lshl_b32 s34, s35, 2
	v_and_b32_e32 v0, 12, v0
	s_add_u32 s34, s10, s34
	v_or_b32_e32 v66, s35, v0
	s_addc_u32 s35, s11, 0
	v_lshlrev_b32_e32 v0, 2, v0
	s_mov_b32 s6, 0
	v_lshl_add_u64 v[68:69], s[34:35], 0, v[0:1]
	v_readlane_b32 s45, v223, 63
	v_readlane_b32 s50, v222, 4
	v_readlane_b32 s51, v222, 5
	v_readlane_b32 s52, v222, 6
	v_readlane_b32 s53, v222, 7
	v_readlane_b32 s54, v222, 8
	v_readlane_b32 s55, v222, 9
	v_readlane_b32 s56, v222, 10
	v_readlane_b32 s57, v222, 11
	v_readlane_b32 s58, v222, 12
	v_readlane_b32 s59, v222, 13
	s_branch .LBB0_756
